# global attention: LDS wait between the two V-fragment read batches replaced by a counted lgkmcnt(8) before the first PV MFMA (both batches in flight), on top of v48
# baseline (speedup 1.0000x reference)
; #define LAS __attribute__((address_space(3)))
; DI unsigned pack2(float lo, float hi) { f32x2 v = {lo, hi}; bf16x2_t b = __builtin_convertvector(v, bf16x2_t); return __builtin_bit_cast(unsigned, b); }
; #define MFMA32(a, b, c) __builtin_amdgcn_mfma_f32_32x32x16_bf16((a), (b), (c), 0, 0, 0)
; DI float fast_exp2(float x) { return __builtin_amdgcn_exp2f(x); }
; template <bool FIRST, bool MASKED>
; DI void attn2_step(f32x16 (&o)[2][2], float (&m_ref)[2], float (&lsum)[2], const bf16x8 (&qf)[2][4], const lchar* Kl, const lchar* Vl, int lane, int kp0, int qw0, float m_init, float l0) {
;     ...
;     bf16x8 pf[2][4];
; #pragma unroll
;     for (int q = 0; q < 2; ++q) {
;         float ps = 0.f;
; #pragma unroll
;         for (int kt = 0; kt < 2; ++kt)
; #pragma unroll
;             for (int i = 0; i < 16; ++i) { const float pv = fast_exp2(sc[q][kt][i]); sc[q][kt][i] = pv; ps += pv; }
;         lsum[q] += ps;
; #pragma unroll
;         for (int s = 0; s < 4; ++s) {
;             u32x4 w;
;             const int kt = s >> 1, b = 8 * (s & 1);
;             w.x = pack2(sc[q][kt][b + 0], sc[q][kt][b + 1]); w.y = pack2(sc[q][kt][b + 2], sc[q][kt][b + 3]);
;             w.z = pack2(sc[q][kt][b + 4], sc[q][kt][b + 5]); w.w = pack2(sc[q][kt][b + 6], sc[q][kt][b + 7]);
;             pf[q][s] = __builtin_bit_cast(bf16x8, w);
;         }
;     }
;     {
;         const int qq = (lane & 15) >> 2, pp = lane & 3, g16 = (lane >> 4) & 1;
;         const lchar* vb = Vl + (4 * h + qq) * VSTR + (16 * g16 + 4 * pp) * 2;
; #pragma unroll
;         for (int s = 0; s < 4; ++s)
; #pragma unroll
;             for (int dt = 0; dt < 2; ++dt) {
;                 const s16x4 lo = __builtin_amdgcn_ds_read_tr16_b64_v4i16((LAS s16x4*)(vb + (16 * s) * VSTR + dt * 64));
;                 const s16x4 hi = __builtin_amdgcn_ds_read_tr16_b64_v4i16((LAS s16x4*)(vb + (16 * s + 8) * VSTR + dt * 64));
;                 const bf16x8 vf = __builtin_shufflevector(lo, hi, 0, 1, 2, 3, 4, 5, 6, 7);
; #pragma unroll
;                 for (int q = 0; q < 2; ++q) o[q][dt] = MFMA32(vf, pf[q][s], o[q][dt]);
;             }
;     }
.LBB0_191:
	v_exp_f32_e32 v112, v112
	v_exp_f32_e32 v113, v113
	v_exp_f32_e32 v114, v114
	v_exp_f32_e32 v115, v115
	v_add_f32_e32 v240, v112, v114
	v_add_f32_e32 v241, v113, v115
	v_exp_f32_e32 v116, v116
	v_exp_f32_e32 v117, v117
	v_exp_f32_e32 v118, v118
	v_exp_f32_e32 v119, v119
	v_add_f32_e32 v240, v240, v116
	v_add_f32_e32 v241, v241, v117
	v_add_f32_e32 v240, v240, v118
	v_add_f32_e32 v241, v241, v119
	v_cvt_pk_bf16_f32 v112, v112, v113
	v_cvt_pk_bf16_f32 v113, v114, v115
	v_cvt_pk_bf16_f32 v114, v116, v117
	v_cvt_pk_bf16_f32 v115, v118, v119
	v_exp_f32_e32 v96, v96
	v_exp_f32_e32 v97, v97
	v_exp_f32_e32 v98, v98
	v_exp_f32_e32 v99, v99
	s_waitcnt lgkmcnt(8)
	v_mfma_f32_32x32x16_bf16 v[32:47], v[208:211], v[112:115], v[32:47]
	v_add_f32_e32 v242, v96, v98
	v_add_f32_e32 v243, v97, v99
	v_exp_f32_e32 v100, v100
	v_exp_f32_e32 v101, v101
	v_exp_f32_e32 v102, v102
	v_exp_f32_e32 v103, v103
	v_add_f32_e32 v242, v242, v100
	v_add_f32_e32 v243, v243, v101
	v_mfma_f32_32x32x16_bf16 v[48:63], v[212:215], v[112:115], v[48:63]
	v_add_f32_e32 v242, v242, v102
	v_add_f32_e32 v243, v243, v103
	v_cvt_pk_bf16_f32 v96, v96, v97
	v_cvt_pk_bf16_f32 v97, v98, v99
	v_cvt_pk_bf16_f32 v98, v100, v101
	v_cvt_pk_bf16_f32 v99, v102, v103
	v_exp_f32_e32 v120, v120
	v_exp_f32_e32 v121, v121
	v_exp_f32_e32 v122, v122
	v_exp_f32_e32 v123, v123
	v_mfma_f32_32x32x16_bf16 v[16:31], v[208:211], v[96:99], v[16:31]
	v_add_f32_e32 v240, v240, v120
	v_add_f32_e32 v241, v241, v121
	v_exp_f32_e32 v124, v124
	v_exp_f32_e32 v125, v125
	v_add_f32_e32 v240, v240, v122
	v_add_f32_e32 v241, v241, v123
	v_exp_f32_e32 v126, v126
	v_exp_f32_e32 v127, v127
	v_add_f32_e32 v240, v240, v124
	v_add_f32_e32 v241, v241, v125
	v_mfma_f32_32x32x16_bf16 v[0:15], v[212:215], v[96:99], v[0:15]
	v_add_f32_e32 v240, v240, v126
	v_add_f32_e32 v241, v241, v127
	v_cvt_pk_bf16_f32 v120, v120, v121
	v_cvt_pk_bf16_f32 v121, v122, v123
	v_cvt_pk_bf16_f32 v122, v124, v125
	v_cvt_pk_bf16_f32 v123, v126, v127
	v_exp_f32_e32 v104, v104
	v_exp_f32_e32 v105, v105
	v_exp_f32_e32 v106, v106
	v_exp_f32_e32 v107, v107
	v_mfma_f32_32x32x16_bf16 v[32:47], v[216:219], v[120:123], v[32:47]
	v_add_f32_e32 v242, v242, v104
	v_add_f32_e32 v243, v243, v105
	v_exp_f32_e32 v108, v108
	v_exp_f32_e32 v109, v109
	v_add_f32_e32 v242, v242, v106
	v_add_f32_e32 v243, v243, v107
	v_exp_f32_e32 v110, v110
	v_exp_f32_e32 v111, v111
	v_add_f32_e32 v242, v242, v108
	v_add_f32_e32 v243, v243, v109
	v_mfma_f32_32x32x16_bf16 v[48:63], v[220:223], v[120:123], v[48:63]
	v_add_f32_e32 v242, v242, v110
	v_add_f32_e32 v243, v243, v111
	v_cvt_pk_bf16_f32 v104, v104, v105
	v_cvt_pk_bf16_f32 v105, v106, v107
	v_cvt_pk_bf16_f32 v106, v108, v109
	v_cvt_pk_bf16_f32 v107, v110, v111
	v_exp_f32_e32 v80, v80
	v_exp_f32_e32 v81, v81
	v_exp_f32_e32 v82, v82
	v_exp_f32_e32 v83, v83
	v_mfma_f32_32x32x16_bf16 v[16:31], v[216:219], v[104:107], v[16:31]
	v_add_f32_e32 v240, v240, v80
	v_add_f32_e32 v241, v241, v81
	v_exp_f32_e32 v84, v84
	v_exp_f32_e32 v85, v85
	v_add_f32_e32 v240, v240, v82
	v_add_f32_e32 v241, v241, v83
	v_exp_f32_e32 v86, v86
	v_exp_f32_e32 v87, v87
	v_add_f32_e32 v240, v240, v84
	v_add_f32_e32 v241, v241, v85
	v_mfma_f32_32x32x16_bf16 v[0:15], v[220:223], v[104:107], v[0:15]
	v_add_f32_e32 v240, v240, v86
	v_add_f32_e32 v241, v241, v87
	v_cvt_pk_bf16_f32 v80, v80, v81
	v_cvt_pk_bf16_f32 v81, v82, v83
	v_cvt_pk_bf16_f32 v82, v84, v85
	v_cvt_pk_bf16_f32 v83, v86, v87
	v_exp_f32_e32 v64, v64
	v_exp_f32_e32 v65, v65
	v_exp_f32_e32 v66, v66
	v_exp_f32_e32 v67, v67
	s_waitcnt lgkmcnt(0)
	v_mfma_f32_32x32x16_bf16 v[32:47], v[224:227], v[80:83], v[32:47]
	v_add_f32_e32 v242, v242, v64
	v_add_f32_e32 v243, v243, v65
	v_exp_f32_e32 v68, v68
	v_exp_f32_e32 v69, v69
	v_add_f32_e32 v242, v242, v66
	v_add_f32_e32 v243, v243, v67
	v_exp_f32_e32 v70, v70
	v_exp_f32_e32 v71, v71
	v_add_f32_e32 v242, v242, v68
	v_add_f32_e32 v243, v243, v69
	v_mfma_f32_32x32x16_bf16 v[48:63], v[228:231], v[80:83], v[48:63]
	v_add_f32_e32 v242, v242, v70
	v_add_f32_e32 v243, v243, v71
	v_cvt_pk_bf16_f32 v64, v64, v65
	v_cvt_pk_bf16_f32 v65, v66, v67
	v_cvt_pk_bf16_f32 v66, v68, v69
	v_cvt_pk_bf16_f32 v67, v70, v71
	v_exp_f32_e32 v88, v88
	v_exp_f32_e32 v89, v89
	v_exp_f32_e32 v90, v90
	v_exp_f32_e32 v91, v91
	v_mfma_f32_32x32x16_bf16 v[16:31], v[224:227], v[64:67], v[16:31]
	v_add_f32_e32 v240, v240, v88
	v_add_f32_e32 v241, v241, v89
	v_exp_f32_e32 v92, v92
	v_exp_f32_e32 v93, v93
	v_add_f32_e32 v240, v240, v90
	v_add_f32_e32 v241, v241, v91
	v_exp_f32_e32 v94, v94
	v_exp_f32_e32 v95, v95
	v_add_f32_e32 v240, v240, v92
	v_add_f32_e32 v241, v241, v93
	v_mfma_f32_32x32x16_bf16 v[0:15], v[228:231], v[64:67], v[0:15]
	v_add_f32_e32 v240, v240, v94
	v_add_f32_e32 v241, v241, v95
	v_cvt_pk_bf16_f32 v88, v88, v89
	v_cvt_pk_bf16_f32 v89, v90, v91
	v_cvt_pk_bf16_f32 v90, v92, v93
	v_cvt_pk_bf16_f32 v91, v94, v95
	v_exp_f32_e32 v72, v72
	v_exp_f32_e32 v73, v73
	v_exp_f32_e32 v74, v74
	v_exp_f32_e32 v75, v75
	v_mfma_f32_32x32x16_bf16 v[32:47], v[232:235], v[88:91], v[32:47]
	v_add_f32_e32 v242, v242, v72
	v_add_f32_e32 v243, v243, v73
	v_exp_f32_e32 v76, v76
	v_exp_f32_e32 v77, v77
	v_add_f32_e32 v242, v242, v74
	v_add_f32_e32 v243, v243, v75
	v_exp_f32_e32 v78, v78
	v_exp_f32_e32 v79, v79
	v_add_f32_e32 v242, v242, v76
	v_add_f32_e32 v243, v243, v77
	v_mfma_f32_32x32x16_bf16 v[48:63], v[236:239], v[88:91], v[48:63]
	v_add_f32_e32 v242, v242, v78
	v_add_f32_e32 v243, v243, v79
	v_cvt_pk_bf16_f32 v72, v72, v73
	v_cvt_pk_bf16_f32 v73, v74, v75
	v_cvt_pk_bf16_f32 v74, v76, v77
	v_cvt_pk_bf16_f32 v75, v78, v79
	s_add_i32 s22, s22, 1
	v_add_f32_e32 v240, v240, v241
	v_add_f32_e32 v242, v242, v243
	s_cmpk_lg_i32 s22, 0x45
	v_add_f32_e32 v183, v183, v240
	v_add_f32_e32 v182, v182, v242
	s_waitcnt lgkmcnt(0)
	s_barrier
	v_mfma_f32_32x32x16_bf16 v[16:31], v[232:235], v[72:75], v[16:31]
	v_mfma_f32_32x32x16_bf16 v[0:15], v[236:239], v[72:75], v[0:15]
	s_cbranch_scc0 .LBB0_194
; template <bool FIRST, bool MASKED>
; DI void attn2_step(f32x16 (&o)[2][2], float (&m_ref)[2], float (&lsum)[2], const bf16x8 (&qf)[2][4], const lchar* Kl, const lchar* Vl, int lane, int kp0, int qw0, float m_init, float l0) {
;     ...
;     bf16x8 kf[4][2];
; #pragma unroll
;     for (int ks = 0; ks < 4; ++ks)
; #pragma unroll
;         for (int kt = 0; kt < 2; ++kt) kf[ks][kt] = *(const LAS bf16x8*)(Kl + (32 * kt + l31) * KSTR + ks * 32 + h * 16);
;     f32x16 sc[2][2];
; #pragma unroll
;     for (int q = 0; q < 2; ++q) {
;         const float init = FIRST ? opaque0() : -m_ref[q];
; #pragma unroll
;         for (int kt = 0; kt < 2; ++kt)
; #pragma unroll
;             for (int i = 0; i < 16; ++i) sc[q][kt][i] = init;
; #pragma unroll
;         for (int ks = 0; ks < 4; ++ks)
; #pragma unroll
;             for (int kt = 0; kt < 2; ++kt) sc[q][kt] = MFMA32(kf[ks][kt], qf[q][ks], sc[q][kt]);
;     }
;     if (MASKED && kp0 >= 0 && !(kp0 >= qw0 + 63 - 128 && kp0 + 63 <= qw0 + 128)) {
; #pragma unroll
;         for (int q = 0; q < 2; ++q) {
;             const int qpos = qw0 + q * 32 + l31;
; #pragma unroll
;             for (int kt = 0; kt < 2; ++kt)
; #pragma unroll
;                 for (int i = 0; i < 16; ++i) {
;                     const int diff = qpos - (kp0 + 32 * kt + crow(i, h));
;                     if (diff > 128 || diff < -128) sc[q][kt][i] = -1e30f;
;                 }
;         }
;     }
;     float mx[2];
; #pragma unroll
;     for (int q = 0; q < 2; ++q) {
;         float m = fmaxf(sc[q][0][0], sc[q][1][0]);
; #pragma unroll
;         for (int i = 1; i < 16; ++i) m = fmaxf(m, fmaxf(sc[q][0][i], sc[q][1][i]));
;         mx[q] = fmaxf(m, shx(m, 32, lane));
;     }
;     if (FIRST) {
; #pragma unroll
;         for (int q = 0; q < 2; ++q) {
;             m_ref[q] = fmaxf(m_init, mx[q]);
;             lsum[q] = (h == 0) ? l0 * fast_exp2(m_init - m_ref[q]) : 0.f;
; #pragma unroll
;             for (int kt = 0; kt < 2; ++kt)
; #pragma unroll
;                 for (int i = 0; i < 16; ++i) sc[q][kt][i] -= m_ref[q];
;         }
;     } else if (__builtin_amdgcn_ballot_w64(fmaxf(mx[0], mx[1]) > ATT_THR) != 0ull) {
; template <bool MASKED> ...
;     ...
;     for (int it = 1; it < ntiles; ++it) {
;         *(LAS u32x4*)(Kbase + ((it + 1) & 1) * KV_K + koff) = rk; *(LAS u32x4*)(Vbase + ((it + 1) & 1) * VB + voff) = rv;
;         const int i2 = min(it + 2, ntiles - 1);
.LBB0_192:
	s_and_b32 s26, s22, 1
	s_mul_i32 s27, s26, 0x2400
	s_add_i32 s23, s22, -1
	v_add_u32_e32 v64, s27, v176
	s_mulk_i32 s26, 0x3000
	s_waitcnt vmcnt(1)
	ds_write_b128 v64, v[162:165]
	v_add_u32_e32 v64, s26, v178
	s_min_i32 s26, s23, 0x41
	s_cmp_lt_u32 s23, 62
	s_cselect_b32 s27, 2, 0xffffffc2
	s_cselect_b32 s36, s1, s2
	s_and_b32 s23, s23, 1
	s_mul_i32 s37, s23, 0x2400
	s_waitcnt vmcnt(0)
	ds_write_b128 v64, v[166:169] offset:18432
	v_or_b32_e32 v64, s37, v128
	v_add_u32_e32 v65, v64, v179
	v_add_u32_e32 v64, v64, v189
	ds_read_b128 v[162:165], v65
	ds_read_b128 v[192:195], v65 offset:32
	ds_read_b128 v[208:211], v64
	ds_read_b128 v[212:215], v64 offset:32
	s_add_i32 s27, s27, s26
	v_xor_b32_e32 v80, 0x80000000, v181
	s_lshl_b32 s26, s27, 6
	v_mov_b32_e32 v81, v80
	v_mov_b64_e32 v[82:83], v[80:81]
	v_mov_b64_e32 v[84:85], v[80:81]
	v_mov_b64_e32 v[86:87], v[80:81]
	v_mov_b64_e32 v[88:89], v[80:81]
	v_mov_b64_e32 v[90:91], v[80:81]
	v_mov_b64_e32 v[92:93], v[80:81]
	v_mov_b64_e32 v[94:95], v[80:81]
	ds_read_b128 v[216:219], v65 offset:64
	ds_read_b128 v[220:223], v65 offset:96
	ds_read_b128 v[224:227], v64 offset:64
	ds_read_b128 v[228:231], v64 offset:96
	s_add_i32 s26, s26, s36
	v_xor_b32_e32 v64, 0x80000000, v180
	s_waitcnt lgkmcnt(7)
	v_mfma_f32_32x32x16_bf16 v[112:127], v[162:165], v[130:133], v[80:95]
	v_add_u32_e32 v166, s26, v188
	v_mov_b32_e32 v65, v64
	v_mov_b64_e32 v[66:67], v[64:65]
	v_mov_b64_e32 v[68:69], v[64:65]
	s_waitcnt lgkmcnt(5)
	v_mfma_f32_32x32x16_bf16 v[80:95], v[208:211], v[130:133], v[80:95]
	v_mov_b64_e32 v[70:71], v[64:65]
	v_mov_b64_e32 v[72:73], v[64:65]
	v_mov_b64_e32 v[74:75], v[64:65]
	v_mov_b64_e32 v[76:77], v[64:65]
	v_mov_b64_e32 v[78:79], v[64:65]
	v_mfma_f32_32x32x16_bf16 v[112:127], v[192:195], v[134:137], v[112:127]
	s_nop 0
	v_mfma_f32_32x32x16_bf16 v[96:111], v[162:165], v[146:149], v[64:79]
	v_mad_i64_i32 v[162:163], s[26:27], s30, v166, 0
	v_lshlrev_b64 v[162:163], 1, v[162:163]
	v_lshl_add_u64 v[164:165], v[184:185], 0, v[162:163]
	v_lshl_add_u64 v[166:167], v[186:187], 0, v[162:163]
	global_load_dwordx4 v[162:165], v[164:165], off
	s_nop 0
	global_load_dwordx4 v[166:169], v[166:167], off
	s_mov_b32 s26, 0x43800000
	s_waitcnt lgkmcnt(4)
	v_mfma_f32_32x32x16_bf16 v[80:95], v[212:215], v[134:137], v[80:95]
	s_waitcnt lgkmcnt(3)
	v_mfma_f32_32x32x16_bf16 v[112:127], v[216:219], v[138:141], v[112:127]
	s_waitcnt lgkmcnt(1)
	v_mfma_f32_32x32x16_bf16 v[80:95], v[224:227], v[138:141], v[80:95]
	v_mfma_f32_32x32x16_bf16 v[64:79], v[208:211], v[146:149], v[64:79]
	v_mfma_f32_32x32x16_bf16 v[112:127], v[220:223], v[142:145], v[112:127]
	s_waitcnt lgkmcnt(0)
	v_mfma_f32_32x32x16_bf16 v[80:95], v[228:231], v[142:145], v[80:95]
	v_mfma_f32_32x32x16_bf16 v[96:111], v[192:195], v[150:153], v[96:111]
	v_mfma_f32_32x32x16_bf16 v[64:79], v[212:215], v[150:153], v[64:79]
	v_mfma_f32_32x32x16_bf16 v[96:111], v[216:219], v[154:157], v[96:111]
	v_mfma_f32_32x32x16_bf16 v[64:79], v[224:227], v[154:157], v[64:79]
	v_mfma_f32_32x32x16_bf16 v[96:111], v[220:223], v[158:161], v[96:111]
	v_mfma_f32_32x32x16_bf16 v[64:79], v[228:231], v[158:161], v[64:79]
	s_mulk_i32 s23, 0x3000
	v_or_b32_e32 v244, s23, v191
	ds_read_b64_tr_b16 v[208:209], v244 offset:18432
	ds_read_b64_tr_b16 v[210:211], v244 offset:19968
	ds_read_b64_tr_b16 v[212:213], v244 offset:18496
	ds_read_b64_tr_b16 v[214:215], v244 offset:20032
	ds_read_b64_tr_b16 v[216:217], v244 offset:21504
	ds_read_b64_tr_b16 v[218:219], v244 offset:23040
	ds_read_b64_tr_b16 v[220:221], v244 offset:21568
	ds_read_b64_tr_b16 v[222:223], v244 offset:23104
	ds_read_b64_tr_b16 v[224:225], v244 offset:24576
	ds_read_b64_tr_b16 v[226:227], v244 offset:26112
	ds_read_b64_tr_b16 v[228:229], v244 offset:24640
	ds_read_b64_tr_b16 v[230:231], v244 offset:26176
	ds_read_b64_tr_b16 v[232:233], v244 offset:27648
	ds_read_b64_tr_b16 v[234:235], v244 offset:29184
	ds_read_b64_tr_b16 v[236:237], v244 offset:27712
	ds_read_b64_tr_b16 v[238:239], v244 offset:29248
	v_max_f32_e32 v194, v240, v242
	v_cmp_lt_f32_e32 vcc, s26, v194
	s_cbranch_vccz .LBB0_191
; DI float fast_exp2(float x) { return __builtin_amdgcn_exp2f(x); }
; template <bool FIRST, bool MASKED>
; DI void attn2_step(f32x16 (&o)[2][2], float (&m_ref)[2], float (&lsum)[2], const bf16x8 (&qf)[2][4], const lchar* Kl, const lchar* Vl, int lane, int kp0, int qw0, float m_init, float l0) {
;     ...
;     } else if (__builtin_amdgcn_ballot_w64(fmaxf(mx[0], mx[1]) > ATT_THR) != 0ull) {
; #pragma unroll
;         for (int q = 0; q < 2; ++q) {
;             const float delta = fmaxf(mx[q], 0.f), alpha = fast_exp2(-delta);
; #pragma unroll
;             for (int dt = 0; dt < 2; ++dt)
; #pragma unroll
;                 for (int i = 0; i < 16; ++i) o[q][dt][i] *= alpha;
;             lsum[q] *= alpha;
; #pragma unroll
;             for (int kt = 0; kt < 2; ++kt)
; #pragma unroll
;                 for (int i = 0; i < 16; ++i) sc[q][kt][i] -= delta;
;             m_ref[q] += delta;
;         }
;     }
	s_nop 15
	v_log_f32_e32 v193, v240
	v_log_f32_e32 v192, v242
	s_nop 1
	v_mov_b32_e32 v194, v193
	v_mov_b32_e32 v195, v192
	s_nop 1
	v_permlane32_swap_b32_e32 v194, v193
	v_permlane32_swap_b32_e32 v195, v192
	s_nop 1
	v_max_f32_e32 v193, v193, v194
	v_max_f32_e32 v192, v192, v195
	v_max_f32_e32 v193, v193, v193
	v_max_f32_e32 v192, v192, v192
	v_max_f32_e32 v194, 0, v193
	v_max_f32_e32 v192, 0, v192
	v_exp_f32_e64 v196, -v194
	v_exp_f32_e64 v200, -v192
	v_pk_add_f32 v[96:97], v[96:97], v[192:193] op_sel_hi:[1,0] neg_lo:[0,1] neg_hi:[0,1]
	v_pk_add_f32 v[98:99], v[98:99], v[192:193] op_sel_hi:[1,0] neg_lo:[0,1] neg_hi:[0,1]
	v_pk_add_f32 v[100:101], v[100:101], v[192:193] op_sel_hi:[1,0] neg_lo:[0,1] neg_hi:[0,1]
	v_pk_mul_f32 v[30:31], v[30:31], v[200:201] op_sel_hi:[1,0]
	v_pk_mul_f32 v[28:29], v[28:29], v[200:201] op_sel_hi:[1,0]
	v_pk_mul_f32 v[26:27], v[26:27], v[200:201] op_sel_hi:[1,0]
	v_pk_mul_f32 v[24:25], v[24:25], v[200:201] op_sel_hi:[1,0]
	v_pk_mul_f32 v[22:23], v[22:23], v[200:201] op_sel_hi:[1,0]
	v_pk_mul_f32 v[20:21], v[20:21], v[200:201] op_sel_hi:[1,0]
	v_pk_mul_f32 v[18:19], v[18:19], v[200:201] op_sel_hi:[1,0]
	v_pk_mul_f32 v[16:17], v[16:17], v[200:201] op_sel_hi:[1,0]
	v_pk_mul_f32 v[14:15], v[14:15], v[200:201] op_sel_hi:[1,0]
	v_pk_mul_f32 v[12:13], v[12:13], v[200:201] op_sel_hi:[1,0]
	v_pk_mul_f32 v[10:11], v[10:11], v[200:201] op_sel_hi:[1,0]
	v_pk_mul_f32 v[8:9], v[8:9], v[200:201] op_sel_hi:[1,0]
	v_pk_mul_f32 v[6:7], v[6:7], v[200:201] op_sel_hi:[1,0]
	v_pk_mul_f32 v[4:5], v[4:5], v[200:201] op_sel_hi:[1,0]
	v_pk_mul_f32 v[2:3], v[2:3], v[200:201] op_sel_hi:[1,0]
	v_pk_mul_f32 v[0:1], v[0:1], v[200:201] op_sel_hi:[1,0]
	v_mov_b32_e32 v201, v196
	v_pk_add_f32 v[102:103], v[102:103], v[192:193] op_sel_hi:[1,0] neg_lo:[0,1] neg_hi:[0,1]
	v_pk_add_f32 v[104:105], v[104:105], v[192:193] op_sel_hi:[1,0] neg_lo:[0,1] neg_hi:[0,1]
	v_pk_add_f32 v[106:107], v[106:107], v[192:193] op_sel_hi:[1,0] neg_lo:[0,1] neg_hi:[0,1]
	v_pk_add_f32 v[108:109], v[108:109], v[192:193] op_sel_hi:[1,0] neg_lo:[0,1] neg_hi:[0,1]
	v_pk_add_f32 v[110:111], v[110:111], v[192:193] op_sel_hi:[1,0] neg_lo:[0,1] neg_hi:[0,1]
	v_pk_add_f32 v[64:65], v[64:65], v[192:193] op_sel_hi:[1,0] neg_lo:[0,1] neg_hi:[0,1]
	v_pk_add_f32 v[66:67], v[66:67], v[192:193] op_sel_hi:[1,0] neg_lo:[0,1] neg_hi:[0,1]
	v_pk_add_f32 v[68:69], v[68:69], v[192:193] op_sel_hi:[1,0] neg_lo:[0,1] neg_hi:[0,1]
	v_pk_add_f32 v[70:71], v[70:71], v[192:193] op_sel_hi:[1,0] neg_lo:[0,1] neg_hi:[0,1]
	v_pk_add_f32 v[72:73], v[72:73], v[192:193] op_sel_hi:[1,0] neg_lo:[0,1] neg_hi:[0,1]
	v_pk_add_f32 v[74:75], v[74:75], v[192:193] op_sel_hi:[1,0] neg_lo:[0,1] neg_hi:[0,1]
	v_pk_add_f32 v[76:77], v[76:77], v[192:193] op_sel_hi:[1,0] neg_lo:[0,1] neg_hi:[0,1]
	v_pk_add_f32 v[78:79], v[78:79], v[192:193] op_sel_hi:[1,0] neg_lo:[0,1] neg_hi:[0,1]
	v_mov_b32_e32 v193, v194
	v_pk_mul_f32 v[46:47], v[46:47], v[196:197] op_sel_hi:[1,0]
	v_pk_mul_f32 v[44:45], v[44:45], v[196:197] op_sel_hi:[1,0]
	v_pk_mul_f32 v[42:43], v[42:43], v[196:197] op_sel_hi:[1,0]
	v_pk_mul_f32 v[40:41], v[40:41], v[196:197] op_sel_hi:[1,0]
	v_pk_mul_f32 v[38:39], v[38:39], v[196:197] op_sel_hi:[1,0]
	v_pk_mul_f32 v[36:37], v[36:37], v[196:197] op_sel_hi:[1,0]
	v_pk_mul_f32 v[34:35], v[34:35], v[196:197] op_sel_hi:[1,0]
	v_pk_mul_f32 v[32:33], v[32:33], v[196:197] op_sel_hi:[1,0]
	v_pk_mul_f32 v[62:63], v[62:63], v[196:197] op_sel_hi:[1,0]
	v_pk_mul_f32 v[60:61], v[60:61], v[196:197] op_sel_hi:[1,0]
	v_pk_mul_f32 v[58:59], v[58:59], v[196:197] op_sel_hi:[1,0]
	v_pk_mul_f32 v[56:57], v[56:57], v[196:197] op_sel_hi:[1,0]
	v_pk_mul_f32 v[54:55], v[54:55], v[196:197] op_sel_hi:[1,0]
	v_pk_mul_f32 v[52:53], v[52:53], v[196:197] op_sel_hi:[1,0]
	v_pk_mul_f32 v[50:51], v[50:51], v[196:197] op_sel_hi:[1,0]
	v_pk_mul_f32 v[48:49], v[48:49], v[196:197] op_sel_hi:[1,0]
	v_pk_add_f32 v[112:113], v[112:113], v[194:195] op_sel_hi:[1,0] neg_lo:[0,1] neg_hi:[0,1]
	v_pk_add_f32 v[114:115], v[114:115], v[194:195] op_sel_hi:[1,0] neg_lo:[0,1] neg_hi:[0,1]
	v_pk_add_f32 v[116:117], v[116:117], v[194:195] op_sel_hi:[1,0] neg_lo:[0,1] neg_hi:[0,1]
	v_pk_add_f32 v[118:119], v[118:119], v[194:195] op_sel_hi:[1,0] neg_lo:[0,1] neg_hi:[0,1]
	v_pk_add_f32 v[120:121], v[120:121], v[194:195] op_sel_hi:[1,0] neg_lo:[0,1] neg_hi:[0,1]
	v_pk_add_f32 v[122:123], v[122:123], v[194:195] op_sel_hi:[1,0] neg_lo:[0,1] neg_hi:[0,1]
	v_pk_add_f32 v[124:125], v[124:125], v[194:195] op_sel_hi:[1,0] neg_lo:[0,1] neg_hi:[0,1]
	v_pk_add_f32 v[126:127], v[126:127], v[194:195] op_sel_hi:[1,0] neg_lo:[0,1] neg_hi:[0,1]
	v_pk_add_f32 v[80:81], v[80:81], v[194:195] op_sel_hi:[1,0] neg_lo:[0,1] neg_hi:[0,1]
	v_pk_add_f32 v[82:83], v[82:83], v[194:195] op_sel_hi:[1,0] neg_lo:[0,1] neg_hi:[0,1]
	v_pk_add_f32 v[84:85], v[84:85], v[194:195] op_sel_hi:[1,0] neg_lo:[0,1] neg_hi:[0,1]
	v_pk_add_f32 v[86:87], v[86:87], v[194:195] op_sel_hi:[1,0] neg_lo:[0,1] neg_hi:[0,1]
	v_pk_add_f32 v[88:89], v[88:89], v[194:195] op_sel_hi:[1,0] neg_lo:[0,1] neg_hi:[0,1]
	v_pk_add_f32 v[90:91], v[90:91], v[194:195] op_sel_hi:[1,0] neg_lo:[0,1] neg_hi:[0,1]
	v_pk_add_f32 v[92:93], v[92:93], v[194:195] op_sel_hi:[1,0] neg_lo:[0,1] neg_hi:[0,1]
	v_pk_add_f32 v[94:95], v[94:95], v[194:195] op_sel_hi:[1,0] neg_lo:[0,1] neg_hi:[0,1]
	v_pk_mul_f32 v[182:183], v[182:183], v[200:201]
	v_pk_add_f32 v[180:181], v[180:181], v[192:193]
	s_branch .LBB0_191
